# strategy 7.4: static s_setprio 1 for waves 4-7 during the attention phase
# speedup vs baseline: 1.0020x; 1.0020x over previous
.LBB0_870:
	s_mov_b64 s[4:5], s[90:91]
	s_cmpk_gt_i32 s25, 0xff
	s_cbranch_scc1 .LBB0_953
	s_add_u32 s26, s4, 0x7a00000
	s_addc_u32 s27, s5, 0
	s_add_u32 s28, s4, 0xba00000
	s_addc_u32 s29, s5, 0
	s_add_u32 s30, s4, 0xfa00000
	s_addc_u32 s31, s5, 0
	s_add_u32 s36, s4, 0x13a00000
	s_addc_u32 s37, s5, 0
	s_lshl_b32 s38, s25, 6
	s_lshl_b32 s39, s24, 6
	v_readfirstlane_b32 s98, v214
	s_nop 3
	s_lshr_b32 s98, s98, 6
	s_cmp_ge_u32 s98, 4
	s_cbranch_scc0 .Lattn_prio_done
	s_setprio 1
.Lattn_prio_done:
	s_branch .LBB0_873
.LBB0_872:
	s_add_i32 s25, s25, s24
	s_add_i32 s38, s38, s39
	s_cmpk_gt_i32 s25, 0xff
	s_cbranch_scc1 .LBB0_953

.LBB0_953:
	s_setprio 0
	s_mov_b64 s[0:1], 0
